# diff-attention P*V block: V fragment LDS reads issued together into separate registers with counted lgkmcnt waits instead of one read + lgkmcnt(0) per MFMA pair
# speedup vs baseline: 1.0453x; 1.0040x over previous
; DI unsigned pack2(float a, float b) { f32v2 v = {a, b}; return __builtin_bit_cast(unsigned, __builtin_convertvector(v, bf16v2)); }
;   DI void tile(const u16* Ks, const u16* Vts) {
;     ...
;       for (int k2 = 0; k2 < 2; ++k2) {
;         u32x4 pk;
;         pk[0] = pack2(s[2 * k2][qb][0], s[2 * k2][qb][1]); pk[1] = pack2(s[2 * k2][qb][2], s[2 * k2][qb][3]);
;         pk[2] = pack2(s[2 * k2 + 1][qb][0], s[2 * k2 + 1][qb][1]); pk[3] = pack2(s[2 * k2 + 1][qb][2], s[2 * k2 + 1][qb][3]);
;         pf[qb][k2] = __builtin_bit_cast(bf16x8, pk);
;       }
;     ...
;     for (int k2 = 0; k2 < 2; ++k2) {
; #pragma unroll
;       for (int d = 0; d < DV / 16; ++d) {
;         const u16* vp = Vts + (d * 16 + fr) * VSTR + k2 * 32 + fq * 4;
;         const uint2 h0 = *reinterpret_cast<const uint2*>(vp);
;         const uint2 h1 = *reinterpret_cast<const uint2*>(vp + 16);
;         const bf16x8 vfv = __builtin_bit_cast(bf16x8, (u32x4{h0.x, h0.y, h1.x, h1.y}));
; #pragma unroll
;         for (int qb = 0; qb < NQB; ++qb) o[qb][d] = __builtin_amdgcn_mfma_f32_16x16x32_bf16(vfv, pf[qb][k2], o[qb][d], 0, 0, 0);
;       }
;     }
.LBB0_205:
	v_cvt_pk_bf16_f32 v30, v122, v123
	v_cvt_pk_bf16_f32 v31, v124, v125
	v_cvt_pk_bf16_f32 v32, v126, v127
	v_cvt_pk_bf16_f32 v33, v128, v129
	v_cvt_pk_bf16_f32 v0, v114, v115
	v_cvt_pk_bf16_f32 v1, v116, v117
	v_cvt_pk_bf16_f32 v2, v118, v119
	v_cvt_pk_bf16_f32 v3, v120, v121
	v_cvt_pk_bf16_f32 v4, v66, v67
	v_cvt_pk_bf16_f32 v5, v68, v69
	v_cvt_pk_bf16_f32 v6, v70, v71
	v_cvt_pk_bf16_f32 v7, v72, v73
	v_cvt_pk_bf16_f32 v98, v74, v75
	v_cvt_pk_bf16_f32 v99, v76, v77
	v_cvt_pk_bf16_f32 v100, v78, v79
	v_cvt_pk_bf16_f32 v101, v80, v81
	s_setprio 1
	v_add3_u32 v70, 16, v198, v200
	v_add_u32_e32 v72, 0x5000, v70
	ds_read2_b64 v[18:21], v72 offset0:32 offset1:36
	v_add_u32_e32 v71, 0x4800, v70
	ds_read2_b64 v[8:11], v71 offset1:4
	v_add_u32_e32 v228, 0x5800, v70
	ds_read2_b64 v[26:29], v228 offset0:64 offset1:68
	v_add_u32_e32 v228, 0x6000, v70
	ds_read2_b64 v[208:211], v228 offset0:96 offset1:100
	v_add_u32_e32 v228, 0x6800, v70
	ds_read2_b64 v[212:215], v228 offset0:128 offset1:132
	v_add_u32_e32 v228, 0x7000, v70
	ds_read2_b64 v[216:219], v228 offset0:160 offset1:164
	v_add_u32_e32 v228, 0x7800, v70
	ds_read2_b64 v[220:223], v228 offset0:192 offset1:196
	v_add_u32_e32 v228, 0x8000, v70
	ds_read2_b64 v[224:227], v228 offset0:224 offset1:228
	s_waitcnt lgkmcnt(7)
	v_mfma_f32_16x16x32_bf16 v[22:25], v[18:21], v[0:3], v[154:157]
	s_nop 2
	v_add_u32_e32 v154, 0x5800, v70
	s_waitcnt lgkmcnt(6)
	v_mfma_f32_16x16x32_bf16 v[12:15], v[8:11], v[0:3], v[158:161]
	v_mfma_f32_16x16x32_bf16 v[8:11], v[8:11], v[4:7], v[174:177]
	s_waitcnt lgkmcnt(5)
	v_mfma_f32_16x16x32_bf16 v[74:77], v[26:29], v[0:3], v[150:153]
	s_nop 2
	v_add_u32_e32 v150, 0x6000, v70
	v_mfma_f32_16x16x32_bf16 v[18:21], v[18:21], v[4:7], v[170:173]
	s_waitcnt lgkmcnt(4)
	v_mfma_f32_16x16x32_bf16 v[78:81], v[208:211], v[0:3], v[146:149]
	s_nop 2
	v_add_u32_e32 v146, 0x6800, v70
	v_mfma_f32_16x16x32_bf16 v[102:105], v[208:211], v[4:7], v[162:165]
	s_waitcnt lgkmcnt(3)
	v_mfma_f32_16x16x32_bf16 v[106:109], v[212:215], v[0:3], v[142:145]
	s_nop 2
	v_add_u32_e32 v142, 0x7000, v70
	v_mfma_f32_16x16x32_bf16 v[94:97], v[212:215], v[4:7], v[94:97]
	s_waitcnt lgkmcnt(2)
	v_mfma_f32_16x16x32_bf16 v[110:113], v[216:219], v[0:3], v[138:141]
	s_nop 2
	v_add_u32_e32 v138, 0x7800, v70
	v_mfma_f32_16x16x32_bf16 v[114:117], v[216:219], v[4:7], v[90:93]
	s_waitcnt lgkmcnt(1)
	v_mfma_f32_16x16x32_bf16 v[118:121], v[220:223], v[0:3], v[134:137]
	s_nop 2
	v_add_u32_e32 v134, 0x8000, v70
	v_mfma_f32_16x16x32_bf16 v[122:125], v[220:223], v[4:7], v[86:89]
	v_mfma_f32_16x16x32_bf16 v[26:29], v[26:29], v[4:7], v[166:169]
	s_waitcnt lgkmcnt(0)
	v_mfma_f32_16x16x32_bf16 v[126:129], v[224:227], v[0:3], v[130:133]
	ds_read2_b64 v[0:3], v71 offset0:8 offset1:12
	v_mfma_f32_16x16x32_bf16 v[130:133], v[224:227], v[4:7], v[82:85]
	ds_read2_b64 v[4:7], v72 offset0:40 offset1:44
	ds_read2_b64 v[208:211], v154 offset0:72 offset1:76
	ds_read2_b64 v[212:215], v150 offset0:104 offset1:108
	ds_read2_b64 v[216:219], v146 offset0:136 offset1:140
	ds_read2_b64 v[220:223], v142 offset0:168 offset1:172
	s_waitcnt lgkmcnt(4)
	v_mfma_f32_16x16x32_bf16 v[70:73], v[4:7], v[30:33], v[22:25]
	v_mfma_f32_16x16x32_bf16 v[18:21], v[4:7], v[98:101], v[18:21]
	s_waitcnt lgkmcnt(3)
	v_mfma_f32_16x16x32_bf16 v[74:77], v[208:211], v[30:33], v[74:77]
	v_mfma_f32_16x16x32_bf16 v[22:25], v[208:211], v[98:101], v[26:29]
	v_mfma_f32_16x16x32_bf16 v[66:69], v[0:3], v[30:33], v[12:15]
	s_nop 1
	ds_read2_b64 v[26:29], v138 offset0:200 offset1:204
	s_waitcnt lgkmcnt(3)
	v_mfma_f32_16x16x32_bf16 v[78:81], v[212:215], v[30:33], v[78:81]
	v_mfma_f32_16x16x32_bf16 v[12:15], v[212:215], v[98:101], v[102:105]
	v_mfma_f32_16x16x32_bf16 v[0:3], v[0:3], v[98:101], v[8:11]
	s_nop 1
	ds_read2_b64 v[102:105], v134 offset0:232 offset1:236
	s_waitcnt lgkmcnt(3)
	v_mfma_f32_16x16x32_bf16 v[82:85], v[216:219], v[30:33], v[106:109]
	v_mfma_f32_16x16x32_bf16 v[8:11], v[216:219], v[98:101], v[94:97]
	s_waitcnt lgkmcnt(2)
	v_mfma_f32_16x16x32_bf16 v[90:93], v[220:223], v[30:33], v[110:113]
	v_mfma_f32_16x16x32_bf16 v[4:7], v[220:223], v[98:101], v[114:117]
	s_waitcnt lgkmcnt(1)
	v_mfma_f32_16x16x32_bf16 v[86:89], v[26:29], v[30:33], v[118:121]
	v_mfma_f32_16x16x32_bf16 v[26:29], v[26:29], v[98:101], v[122:125]
	s_waitcnt lgkmcnt(0)
	v_mfma_f32_16x16x32_bf16 v[94:97], v[102:105], v[30:33], v[126:129]
	v_mfma_f32_16x16x32_bf16 v[30:33], v[102:105], v[98:101], v[130:133]
	s_setprio 0
	v_mov_b32_e32 v197, v201
	v_mov_b32_e32 v201, v203
	v_mov_b32_e32 v202, v204
	v_mov_b32_e32 v115, v199
